# work-queue loop heads: redundant barrier in front of the item fetch removed (fetch overlaps the other waves' item tails)
# speedup vs baseline: 1.0098x; 1.0098x over previous
.LBB0_544:
	s_and_saveexec_b64 s[0:1], s[14:15]
	s_cbranch_execz .LBB0_548
	v_cmp_le_i32_e32 vcc, 0, v255
	s_cbranch_vccnz .Lar_static
	v_mov_b32_e32 v255, 1
	global_atomic_add v255, v3, v255, s[66:67] sc0
	s_waitcnt vmcnt(0)
	v_add_u32_e32 v0, 0x400, v255
	v_mov_b32_e32 v255, -1
	s_branch .Lar_have

.LBB0_898:
	s_and_saveexec_b64 s[0:1], s[14:15]
	s_cbranch_execz .LBB0_902
	s_mov_b64 s[6:7], exec
	v_mbcnt_lo_u32_b32 v0, s6, 0
	v_mbcnt_hi_u32_b32 v0, s7, v0
	v_cmp_eq_u32_e32 vcc, 0, v0
	s_and_saveexec_b64 s[4:5], vcc
	s_cbranch_execz .LBB0_901
	s_bcnt1_i32_b64 s6, s[6:7]
	v_mov_b32_e32 v1, s6
	global_atomic_add v1, v3, v1, s[66:67] offset:4 sc0
